# mate-asymmetric s_setprio 1 (by LDS_ALLOC base) in GEMM phases to break lockstep of CU-mates
# baseline (speedup 1.0000x reference)
.LBB0_69:
	s_or_b64 exec, exec, s[4:5]
	v_and_b32_e32 v1, 0x3ff, v0
	s_barrier
	s_getreg_b32 s3, hwreg(HW_REG_LDS_ALLOC, 0, 12)
	s_cmp_eq_u32 s3, 0
	s_cbranch_scc1 .Lmateprio_1
	s_setprio 1
.Lmateprio_1:
.LBB0_70:
	v_and_b32_e32 v2, 7, v1
	s_cmpk_lt_u32 s2, 0x1b00
	v_cmp_gt_u32_e64 s[6:7], 4, v2
	s_cselect_b64 s[8:9], -1, 0
	v_readfirstlane_b32 s4, v1
	s_and_saveexec_b64 s[60:61], s[8:9]
	s_cbranch_execz .LBB0_148
	s_load_dword s8, s[0:1], 0x1b8
	s_and_b32 s3, s2, 7
	v_lshrrev_b32_e32 v3, 3, v1
	v_lshlrev_b32_e32 v4, 4, v1
	v_mul_u32_u24_e32 v5, 0x48, v3
	s_waitcnt lgkmcnt(0)
	s_lshr_b32 s33, s8, 3
	s_add_u32 s94, s82, 0xd6c0200
	s_addc_u32 s95, s83, 0
	s_add_u32 s14, s82, 0x10bc0100
	s_addc_u32 s15, s83, 0
	s_add_u32 s68, s82, 0x12bc0100
	v_and_b32_e32 v4, 0x70, v4
	s_addc_u32 s69, s83, 0
	v_lshl_add_u32 v174, v5, 1, v4
	v_lshlrev_b32_e32 v5, 6, v1
	s_add_u32 s70, s82, 0x16bc0100
	v_and_b32_e32 v177, 64, v5
	s_addc_u32 s71, s83, 0
	v_lshrrev_b32_e32 v176, 1, v1
	v_lshlrev_b32_e32 v5, 2, v177
	s_movk_i32 s9, 0x204
	s_add_u32 s10, s82, 0x18bc0100
	v_mad_u32_u24 v178, v176, s9, v5
	v_lshlrev_b32_e32 v5, 2, v1
	v_mov_b32_e32 v143, 0
	v_lshlrev_b32_e32 v142, 11, v3
	s_addc_u32 s11, s83, 0
	v_and_b32_e32 v179, 0x7c, v5
	v_lshl_add_u64 v[10:11], s[92:93], 0, v[142:143]
	v_mov_b32_e32 v5, v143
	v_writelane_b32 v252, s10, 28
	v_lshl_add_u64 v[144:145], v[10:11], 0, v[4:5]
	v_lshl_add_u64 v[10:11], s[82:83], 0, v[142:143]
	v_writelane_b32 v252, s11, 29
	s_bfe_u32 s10, s4, 0x10006
	s_lshr_b32 s4, s4, 1
	v_lshl_add_u64 v[146:147], v[10:11], 0, v[4:5]
	v_bfe_u32 v3, v1, 5, 1
	v_and_b32_e32 v5, 31, v1
	s_and_b32 s11, s4, 0x7fffffc0
	v_lshlrev_b32_e32 v4, 4, v3
	v_or_b32_e32 v7, s11, v5
	s_movk_i32 s12, 0x90
	v_mad_u64_u32 v[148:149], s[4:5], v7, s12, v[4:5]
	v_lshl_or_b32 v7, s10, 6, v5
	v_lshl_or_b32 v3, v3, 2, s11
	v_lshrrev_b32_e32 v153, 5, v1
	v_mad_u32_u24 v149, v7, s12, v4
	v_mul_lo_u32 v3, v3, s9
	s_lshl_b32 s4, s10, 8
	v_lshlrev_b32_e32 v4, 2, v5
	v_lshrrev_b32_e32 v180, 4, v1
	v_add3_u32 v181, s4, v3, v4
	v_mul_lo_u32 v3, v153, s9
	v_lshl_add_u32 v182, v5, 4, v3
	v_mul_lo_u32 v3, v180, s9
	v_and_b32_e32 v4, 15, v1
	v_lshl_add_u32 v184, v4, 5, v3
	v_lshlrev_b32_e32 v150, 4, v4
	v_lshlrev_b32_e32 v4, 5, v1
	v_lshlrev_b32_e32 v6, 3, v2
	v_and_b32_e32 v4, 0x100, v4
	v_xor_b32_e32 v8, 32, v6
	v_add_u32_e32 v3, v3, v4
	v_and_b32_e32 v1, 3, v1
	v_add_u32_e32 v175, 0x9000, v174
	s_lshr_b32 s44, s2, 3
	s_and_b32 s45, s2, -8
	s_and_b32 s46, s8, -8
	v_add_u32_e32 v183, 8, v153
	v_mov_b32_e32 v151, v143
	v_add_u32_e32 v185, 16, v180
	v_lshl_add_u32 v186, v8, 2, v3
	v_lshl_add_u32 v187, v2, 5, v3
	v_lshlrev_b32_e32 v152, 6, v1
	v_mov_b32_e32 v1, v143
	s_mov_b32 s27, 0
	s_mov_b32 s47, 0x10000
	s_mov_b32 s87, 0x20000
	s_mov_b32 s10, 0x30000
	v_mov_b32_e32 v188, 0x358637bd
	s_mov_b32 s11, 0x800000
	s_movk_i32 s20, 0x7fff
	s_mov_b32 s21, 0x3f317217
	s_mov_b32 s96, 0x7f800000
	s_mov_b64 s[28:29], 0x80
	s_mov_b64 s[30:31], 0xae40000
	v_lshlrev_b32_e32 v154, 2, v6
	v_lshlrev_b32_e32 v156, 2, v8
	s_mov_b64 s[34:35], 0xaec0000
	s_mov_b32 s97, 0xaec0000
	s_mov_b64 s[36:37], 0x2000
	v_add_u32_e32 v189, 0x4000, v181
	v_add_u32_e32 v190, 0x400, v181
	v_add_u32_e32 v191, 0x4400, v181
	v_add_u32_e32 v192, 0x1000, v181
	v_add_u32_e32 v193, 0x5000, v181
	v_add_u32_e32 v194, 0x1400, v181
	v_add_u32_e32 v195, 0x5400, v181
	v_add_u32_e32 v196, 0x2000, v181
	v_add_u32_e32 v197, 0x6000, v181
	v_add_u32_e32 v198, 0x2400, v181
	v_add_u32_e32 v199, 0x6400, v181
	v_add_u32_e32 v200, 0x3000, v181
	v_add_u32_e32 v201, 0x7000, v181
	v_add_u32_e32 v202, 0x3400, v181
	v_add_u32_e32 v203, 0x7400, v181
	v_mov_b32_e32 v204, 1
	v_mov_b32_e32 v205, 0x41b17218
	v_mbcnt_lo_u32_b32 v206, -1, 0
	s_branch .LBB0_73

.LBB0_163:
	s_or_b64 exec, exec, s[4:5]
	v_and_b32_e32 v147, 0x3ff, v0
	s_barrier
	s_setprio 0

.LBB0_296:
	s_or_b64 exec, exec, s[4:5]
	v_and_b32_e32 v2, 0x3ff, v0
	s_barrier
	s_getreg_b32 s3, hwreg(HW_REG_LDS_ALLOC, 0, 12)
	s_cmp_eq_u32 s3, 0
	s_cbranch_scc1 .Lmateprio_3
	s_setprio 1
.Lmateprio_3:
.LBB0_297:
	s_cmpk_gt_u32 s2, 0x7ff
	v_readfirstlane_b32 s4, v2
	s_cbranch_scc1 .LBB0_321
	s_add_u32 s10, s82, 0xae60000
	v_lshrrev_b32_e32 v1, 5, v2
	s_addc_u32 s11, s83, 0
	v_bfe_u32 v3, v2, 5, 1
	v_and_b32_e32 v6, 31, v2
	s_bfe_u32 s6, s4, 0x10006
	v_lshrrev_b32_e32 v5, 3, v2
	v_lshlrev_b32_e32 v2, 4, v2
	s_lshr_b32 s4, s4, 1
	s_load_dwordx16 s[60:75], s[0:1], 0x0
	s_load_dword s12, s[0:1], 0x1b8
	v_mul_u32_u24_e32 v4, 0x48, v5
	v_and_b32_e32 v2, 0x70, v2
	s_and_b32 s7, s4, 0x7fffffc0
	v_lshl_add_u32 v90, v4, 1, v2
	v_or_b32_e32 v7, s7, v6
	v_lshlrev_b32_e32 v4, 4, v3
	s_movk_i32 s13, 0x90
	v_mad_u64_u32 v[66:67], s[4:5], v7, s13, v[4:5]
	v_lshl_or_b32 v3, v3, 2, s7
	s_movk_i32 s14, 0x204
	v_mul_lo_u32 v3, v3, s14
	s_lshl_b32 s4, s6, 8
	v_lshlrev_b32_e32 v92, 2, v6
	v_lshl_or_b32 v7, s6, 6, v6
	v_add3_u32 v93, s4, v3, v92
	v_lshlrev_b32_e32 v68, 11, v5
	v_mov_b32_e32 v69, 0
	v_readlane_b32 s4, v252, 0
	s_waitcnt lgkmcnt(0)
	s_mov_b64 s[48:49], s[64:65]
	s_and_b32 s3, s2, 7
	s_lshr_b32 s16, s12, 3
	s_lshr_b32 s17, s2, 3
	v_mad_u32_u24 v67, v7, s13, v4
	v_lshl_add_u64 v[4:5], s[84:85], 0, v[68:69]
	v_mov_b32_e32 v3, v69
	v_readlane_b32 s5, v252, 1
	s_mov_b64 s[50:51], s[66:67]
	v_lshl_add_u64 v[70:71], v[4:5], 0, v[2:3]
	v_lshl_add_u64 v[4:5], s[4:5], 0, v[68:69]
	s_cmp_lg_u64 s[50:51], 0
	v_lshl_add_u64 v[72:73], v[4:5], 0, v[2:3]
	s_cselect_b64 s[4:5], -1, 0
	v_mul_lo_u32 v2, v1, s14
	v_lshl_add_u32 v94, v6, 4, v2
	v_cndmask_b32_e64 v2, 0, 1, s[4:5]
	v_add_u32_e32 v91, 0x9000, v90
	s_mov_b32 s13, 0
	v_cmp_eq_u32_e64 s[6:7], 0, v6
	s_mov_b64 s[44:45], s[60:61]
	s_and_b32 s18, s2, -8
	s_and_b32 s19, s12, -8
	s_mov_b32 s20, 0x10000
	s_mov_b32 s21, 0x20000
	s_mov_b32 s22, 0x30000
	v_cmp_ne_u32_e64 s[4:5], 1, v2
	s_lshl_b32 s23, s3, 7
	s_movk_i32 s24, 0x7fff
	v_add_u32_e32 v95, 0x4000, v93
	v_add_u32_e32 v96, 0x400, v93
	v_add_u32_e32 v97, 0x4400, v93
	v_add_u32_e32 v98, 0x1000, v93
	v_add_u32_e32 v99, 0x5000, v93
	v_add_u32_e32 v100, 0x1400, v93
	v_add_u32_e32 v101, 0x5400, v93
	v_add_u32_e32 v102, 0x2000, v93
	v_add_u32_e32 v103, 0x6000, v93
	v_add_u32_e32 v104, 0x2400, v93
	v_add_u32_e32 v105, 0x6400, v93
	v_add_u32_e32 v106, 0x3000, v93
	v_add_u32_e32 v107, 0x7000, v93
	v_add_u32_e32 v108, 0x3400, v93
	v_add_u32_e32 v109, 0x7400, v93
	v_mbcnt_lo_u32_b32 v110, -1, 0
	v_mov_b32_e32 v111, 1
	s_branch .LBB0_300

.LBB0_467:
	s_or_b64 exec, exec, s[4:5]
	v_and_b32_e32 v1, 0x3ff, v0
	s_barrier
	s_setprio 0

.Lmateprio_8:
.LBB0_560:
	s_cmpk_gt_u32 s2, 0x7ff
	v_readfirstlane_b32 s4, v2
	s_cbranch_scc1 .LBB0_573
	s_add_u32 s8, s18, 0x1000
	s_addc_u32 s9, s19, 0
	s_add_u32 s10, s82, 0xaea0000
	s_addc_u32 s11, s83, 0
	v_lshrrev_b32_e32 v1, 5, v2
	v_bfe_u32 v3, v2, 5, 1
	v_and_b32_e32 v6, 31, v2
	s_bfe_u32 s13, s4, 0x10006
	v_lshrrev_b32_e32 v5, 3, v2
	v_lshlrev_b32_e32 v2, 4, v2
	s_lshr_b32 s4, s4, 1
	v_mul_u32_u24_e32 v4, 0x48, v5
	v_and_b32_e32 v2, 0x70, v2
	s_and_b32 s16, s4, 0x7fffffc0
	v_lshl_add_u32 v90, v4, 1, v2
	v_or_b32_e32 v7, s16, v6
	v_lshlrev_b32_e32 v4, 4, v3
	s_movk_i32 s17, 0x90
	v_mad_u64_u32 v[66:67], s[4:5], v7, s17, v[4:5]
	v_lshl_or_b32 v3, v3, 2, s16
	s_movk_i32 s16, 0x204
	v_mul_lo_u32 v3, v3, s16
	s_lshl_b32 s4, s13, 8
	v_lshlrev_b32_e32 v92, 2, v6
	v_lshl_or_b32 v7, s13, 6, v6
	v_add3_u32 v93, s4, v3, v92
	v_lshlrev_b32_e32 v68, 11, v5
	v_mov_b32_e32 v69, 0
	v_readlane_b32 s4, v252, 4
	v_mad_u32_u24 v67, v7, s17, v4
	v_lshl_add_u64 v[4:5], s[84:85], 0, v[68:69]
	v_mov_b32_e32 v3, v69
	v_readlane_b32 s5, v252, 5
	v_lshl_add_u64 v[70:71], v[4:5], 0, v[2:3]
	s_load_dword s12, s[0:1], 0x1b8
	v_lshl_add_u64 v[4:5], s[4:5], 0, v[68:69]
	v_lshl_add_u64 v[72:73], v[4:5], 0, v[2:3]
	v_mbcnt_lo_u32_b32 v2, -1, 0
	v_mbcnt_hi_u32_b32 v2, -1, v2
	v_and_b32_e32 v4, 64, v2
	v_xor_b32_e32 v3, 1, v2
	v_add_u32_e32 v4, 64, v4
	v_cmp_lt_i32_e64 s[4:5], v3, v4
	s_and_b32 s3, s2, 7
	s_waitcnt lgkmcnt(0)
	s_lshr_b32 s14, s12, 3
	v_cndmask_b32_e64 v3, v2, v3, s[4:5]
	v_lshlrev_b32_e32 v94, 2, v3
	v_xor_b32_e32 v3, 2, v2
	v_cmp_lt_i32_e64 s[4:5], v3, v4
	s_lshr_b32 s15, s2, 3
	v_add_u32_e32 v91, 0x9000, v90
	v_cndmask_b32_e64 v3, v2, v3, s[4:5]
	v_lshlrev_b32_e32 v95, 2, v3
	v_xor_b32_e32 v3, 4, v2
	v_cmp_lt_i32_e64 s[4:5], v3, v4
	s_mov_b32 s13, 0
	v_cmp_eq_u32_e32 vcc, 0, v6
	v_cndmask_b32_e64 v3, v2, v3, s[4:5]
	v_lshlrev_b32_e32 v96, 2, v3
	v_xor_b32_e32 v3, 8, v2
	v_cmp_lt_i32_e64 s[4:5], v3, v4
	s_and_b32 s17, s12, -8
	s_lshl_b32 s18, s3, 7
	v_cndmask_b32_e64 v3, v2, v3, s[4:5]
	v_lshlrev_b32_e32 v97, 2, v3
	v_xor_b32_e32 v3, 16, v2
	v_cmp_lt_i32_e64 s[4:5], v3, v4
	s_mov_b32 s19, 0x10000
	s_mov_b32 s20, 0x20000
	v_cndmask_b32_e64 v2, v2, v3, s[4:5]
	v_lshlrev_b32_e32 v98, 2, v2
	v_mul_lo_u32 v2, v1, s16
	v_lshl_add_u32 v99, v6, 4, v2
	s_and_b32 s16, s2, -8
	s_mov_b32 s21, 0x30000
	s_movk_i32 s22, 0x7fff
	v_add_u32_e32 v100, 0x4000, v93
	v_add_u32_e32 v101, 0x400, v93
	v_add_u32_e32 v102, 0x4400, v93
	v_add_u32_e32 v103, 0x1000, v93
	v_add_u32_e32 v104, 0x5000, v93
	v_add_u32_e32 v105, 0x1400, v93
	v_add_u32_e32 v106, 0x5400, v93
	v_add_u32_e32 v107, 0x2000, v93
	v_add_u32_e32 v108, 0x6000, v93
	v_add_u32_e32 v109, 0x2400, v93
	v_add_u32_e32 v110, 0x6400, v93
	v_add_u32_e32 v111, 0x3000, v93
	v_add_u32_e32 v112, 0x7000, v93
	v_add_u32_e32 v113, 0x3400, v93
	v_add_u32_e32 v114, 0x7400, v93
	v_mov_b32_e32 v115, 1
	s_branch .LBB0_563
